# r53 + NSA compressed-KV staging: all iterations' global loads issued up front (single wait), with code-alignment parity of the following phases preserved
# baseline (speedup 1.0000x reference)
.LBB0_683:
	s_nop 0
	s_or_b64 exec, exec, s[0:1]
	v_and_b32_e32 v70, 63, v1
	v_cmp_eq_u32_e64 s[0:1], 0, v1
	s_and_saveexec_b64 s[2:3], s[0:1]
	v_mov_b32_e32 v2, s87
	ds_write_b32 v2, v0
	s_or_b64 exec, exec, s[2:3]
	v_and_b32_e32 v107, 16, v15
	v_add_u32_e32 v10, 0, v107
	s_movk_i32 s2, 0x90
	v_mad_u32_u24 v11, v66, s2, v10
	s_waitcnt lgkmcnt(0)
	s_barrier
	ds_read_b128 v[2:5], v11 offset:35840
	ds_read_b128 v[6:9], v11 offset:35872
	s_waitcnt vmcnt(2) lgkmcnt(1)
	v_mfma_f32_32x32x16_bf16 v[50:65], v[2:5], v[88:91], 0
	ds_read_b128 v[2:5], v11 offset:35904
	v_mul_u32_u24_e32 v148, 0x90, v66
	s_cmp_gt_u32 s78, 7
	s_cselect_b64 s[2:3], -1, 0
	s_cmp_lt_u32 s78, 8
	v_add_u32_e32 v72, v10, v148
	v_mov_b32_e32 v18, 0
	s_waitcnt lgkmcnt(1)
	v_mfma_f32_32x32x16_bf16 v[50:65], v[6:9], v[80:83], v[50:65]
	v_mov_b32_e32 v19, 0
	v_mov_b32_e32 v20, 0
	v_mov_b32_e32 v21, 0
	v_mov_b32_e32 v22, 0
	v_mov_b32_e32 v23, 0
	v_mov_b32_e32 v24, 0
	v_mov_b32_e32 v25, 0
	s_waitcnt lgkmcnt(0)
	v_mfma_f32_32x32x16_bf16 v[50:65], v[2:5], v[84:87], v[50:65]
	ds_read_b128 v[2:5], v11 offset:35936
	v_mov_b32_e32 v26, 0
	v_mov_b32_e32 v27, 0
	v_mov_b32_e32 v28, 0
	v_mov_b32_e32 v29, 0
	v_mov_b32_e32 v30, 0
	v_mov_b32_e32 v31, 0
	s_waitcnt vmcnt(1) lgkmcnt(0)
	v_mfma_f32_32x32x16_bf16 v[50:65], v[2:5], v[92:95], v[50:65]
	ds_read_b128 v[2:5], v11 offset:54272
	v_mov_b32_e32 v32, 0
	v_mov_b32_e32 v33, 0
	s_waitcnt lgkmcnt(0)
	v_mfma_f32_32x32x16_bf16 v[50:65], v[2:5], v[88:91], v[50:65]
	ds_read_b128 v[2:5], v11 offset:54304
	ds_read_b128 v[214:217], v11 offset:54336
	s_waitcnt lgkmcnt(1)
	v_mfma_f32_32x32x16_bf16 v[50:65], v[2:5], v[80:83], v[50:65]
	ds_read_b128 v[2:5], v11 offset:54368
	s_waitcnt lgkmcnt(1)
	v_mfma_f32_32x32x16_bf16 v[50:65], v[214:217], v[84:87], v[50:65]
	s_waitcnt lgkmcnt(0)
	v_mfma_f32_32x32x16_bf16 v[50:65], v[2:5], v[92:95], v[50:65]
	v_mov_b32_e32 v2, 0
	s_cbranch_scc1 .LBB0_687
	ds_read_b128 v[4:7], v72 offset:40448
	ds_read_b128 v[214:217], v72 offset:40480
	s_waitcnt lgkmcnt(1)
	v_mfma_f32_32x32x16_bf16 v[18:33], v[4:7], v[88:91], 0
	ds_read_b128 v[4:7], v72 offset:40512
	s_waitcnt lgkmcnt(1)
	v_mfma_f32_32x32x16_bf16 v[18:33], v[214:217], v[80:83], v[18:33]
	ds_read_b128 v[214:217], v72 offset:40544
	s_waitcnt lgkmcnt(1)
	v_mfma_f32_32x32x16_bf16 v[18:33], v[4:7], v[84:87], v[18:33]
	ds_read_b128 v[4:7], v72 offset:58880
	s_waitcnt lgkmcnt(1)
	v_mfma_f32_32x32x16_bf16 v[18:33], v[214:217], v[92:95], v[18:33]
	ds_read_b128 v[214:217], v72 offset:58912
	s_waitcnt lgkmcnt(1)
	v_mfma_f32_32x32x16_bf16 v[18:33], v[4:7], v[88:91], v[18:33]
	ds_read_b128 v[4:7], v72 offset:58944
	s_waitcnt lgkmcnt(1)
	v_mfma_f32_32x32x16_bf16 v[18:33], v[214:217], v[80:83], v[18:33]
	ds_read_b128 v[214:217], v72 offset:58976
	s_waitcnt lgkmcnt(1)
	v_mfma_f32_32x32x16_bf16 v[18:33], v[4:7], v[84:87], v[18:33]
	s_waitcnt lgkmcnt(0)
	v_mfma_f32_32x32x16_bf16 v[18:33], v[214:217], v[92:95], v[18:33]
